# prep: x -> bf16 conversion as a 32-load stream with 16 loads in flight behind counted vmcnt waits (was one load per iteration with vmcnt(0))
# speedup vs baseline: 1.0189x; 1.0075x over previous
.LBB0_5:
	s_or_b64 exec, exec, s[6:7]
	s_ashr_i32 s3, s2, 31
	s_lshl_b64 s[6:7], s[2:3], 9
	v_mov_b32_e32 v165, 0
	v_lshl_add_u64 v[2:3], s[6:7], 0, v[164:165]
	s_mov_b64 s[6:7], 0x400000
	v_cmp_gt_u64_e32 vcc, s[6:7], v[2:3]
	s_and_saveexec_b64 s[6:7], vcc
	s_cbranch_execz .LBB0_8
	s_ashr_i32 s13, s30, 31
	s_mov_b32 s12, s30
	s_lshl_b64 s[8:9], s[12:13], 9
	s_lshl_b64 s[10:11], s[2:3], 13
	s_add_u32 s10, s68, s10
	v_lshlrev_b32_e32 v4, 4, v164
	v_mov_b32_e32 v5, v165
	s_addc_u32 s11, s69, s11
	v_lshl_add_u64 v[4:5], s[10:11], 0, v[4:5]
	s_lshl_b64 s[10:11], s[12:13], 13
	s_lshl_b64 s[14:15], s[2:3], 12
	s_add_u32 s14, s28, s14
	v_lshlrev_b32_e32 v6, 3, v164
	v_mov_b32_e32 v7, v165
	s_addc_u32 s15, s29, s15
	v_lshl_add_u64 v[6:7], s[14:15], 0, v[6:7]
	s_mov_b64 s[14:15], 0xbc00000
	v_lshl_add_u64 v[6:7], v[6:7], 0, s[14:15]
	s_lshl_b64 s[12:13], s[12:13], 12
	s_mov_b64 s[14:15], 0
	s_mov_b64 s[16:17], 0x3fffff
	global_load_dwordx4 v[26:29], v[4:5], off
	v_lshl_add_u64 v[4:5], v[4:5], 0, s[10:11]
	global_load_dwordx4 v[30:33], v[4:5], off
	v_lshl_add_u64 v[4:5], v[4:5], 0, s[10:11]
	global_load_dwordx4 v[34:37], v[4:5], off
	v_lshl_add_u64 v[4:5], v[4:5], 0, s[10:11]
	global_load_dwordx4 v[38:41], v[4:5], off
	v_lshl_add_u64 v[4:5], v[4:5], 0, s[10:11]
	global_load_dwordx4 v[42:45], v[4:5], off
	v_lshl_add_u64 v[4:5], v[4:5], 0, s[10:11]
	global_load_dwordx4 v[46:49], v[4:5], off
	v_lshl_add_u64 v[4:5], v[4:5], 0, s[10:11]
	global_load_dwordx4 v[50:53], v[4:5], off
	v_lshl_add_u64 v[4:5], v[4:5], 0, s[10:11]
	global_load_dwordx4 v[54:57], v[4:5], off
	v_lshl_add_u64 v[4:5], v[4:5], 0, s[10:11]
	global_load_dwordx4 v[58:61], v[4:5], off
	v_lshl_add_u64 v[4:5], v[4:5], 0, s[10:11]
	global_load_dwordx4 v[62:65], v[4:5], off
	v_lshl_add_u64 v[4:5], v[4:5], 0, s[10:11]
	global_load_dwordx4 v[66:69], v[4:5], off
	v_lshl_add_u64 v[4:5], v[4:5], 0, s[10:11]
	global_load_dwordx4 v[70:73], v[4:5], off
	v_lshl_add_u64 v[4:5], v[4:5], 0, s[10:11]
	global_load_dwordx4 v[74:77], v[4:5], off
	v_lshl_add_u64 v[4:5], v[4:5], 0, s[10:11]
	global_load_dwordx4 v[78:81], v[4:5], off
	v_lshl_add_u64 v[4:5], v[4:5], 0, s[10:11]
	global_load_dwordx4 v[82:85], v[4:5], off
	v_lshl_add_u64 v[4:5], v[4:5], 0, s[10:11]
	global_load_dwordx4 v[86:89], v[4:5], off
	v_lshl_add_u64 v[4:5], v[4:5], 0, s[10:11]
	s_waitcnt vmcnt(15)
	v_cvt_pk_bf16_f32 v26, v26, v27
	v_cvt_pk_bf16_f32 v27, v28, v29
	global_store_dwordx2 v[6:7], v[26:27], off
	v_lshl_add_u64 v[6:7], v[6:7], 0, s[12:13]
	global_load_dwordx4 v[26:29], v[4:5], off
	v_lshl_add_u64 v[4:5], v[4:5], 0, s[10:11]
	s_waitcnt vmcnt(16)
	v_cvt_pk_bf16_f32 v30, v30, v31
	v_cvt_pk_bf16_f32 v31, v32, v33
	global_store_dwordx2 v[6:7], v[30:31], off
	v_lshl_add_u64 v[6:7], v[6:7], 0, s[12:13]
	global_load_dwordx4 v[30:33], v[4:5], off
	v_lshl_add_u64 v[4:5], v[4:5], 0, s[10:11]
	s_waitcnt vmcnt(17)
	v_cvt_pk_bf16_f32 v34, v34, v35
	v_cvt_pk_bf16_f32 v35, v36, v37
	global_store_dwordx2 v[6:7], v[34:35], off
	v_lshl_add_u64 v[6:7], v[6:7], 0, s[12:13]
	global_load_dwordx4 v[34:37], v[4:5], off
	v_lshl_add_u64 v[4:5], v[4:5], 0, s[10:11]
	s_waitcnt vmcnt(18)
	v_cvt_pk_bf16_f32 v38, v38, v39
	v_cvt_pk_bf16_f32 v39, v40, v41
	global_store_dwordx2 v[6:7], v[38:39], off
	v_lshl_add_u64 v[6:7], v[6:7], 0, s[12:13]
	global_load_dwordx4 v[38:41], v[4:5], off
	v_lshl_add_u64 v[4:5], v[4:5], 0, s[10:11]
	s_waitcnt vmcnt(19)
	v_cvt_pk_bf16_f32 v42, v42, v43
	v_cvt_pk_bf16_f32 v43, v44, v45
	global_store_dwordx2 v[6:7], v[42:43], off
	v_lshl_add_u64 v[6:7], v[6:7], 0, s[12:13]
	global_load_dwordx4 v[42:45], v[4:5], off
	v_lshl_add_u64 v[4:5], v[4:5], 0, s[10:11]
	s_waitcnt vmcnt(20)
	v_cvt_pk_bf16_f32 v46, v46, v47
	v_cvt_pk_bf16_f32 v47, v48, v49
	global_store_dwordx2 v[6:7], v[46:47], off
	v_lshl_add_u64 v[6:7], v[6:7], 0, s[12:13]
	global_load_dwordx4 v[46:49], v[4:5], off
	v_lshl_add_u64 v[4:5], v[4:5], 0, s[10:11]
	s_waitcnt vmcnt(21)
	v_cvt_pk_bf16_f32 v50, v50, v51
	v_cvt_pk_bf16_f32 v51, v52, v53
	global_store_dwordx2 v[6:7], v[50:51], off
	v_lshl_add_u64 v[6:7], v[6:7], 0, s[12:13]
	global_load_dwordx4 v[50:53], v[4:5], off
	v_lshl_add_u64 v[4:5], v[4:5], 0, s[10:11]
	s_waitcnt vmcnt(22)
	v_cvt_pk_bf16_f32 v54, v54, v55
	v_cvt_pk_bf16_f32 v55, v56, v57
	global_store_dwordx2 v[6:7], v[54:55], off
	v_lshl_add_u64 v[6:7], v[6:7], 0, s[12:13]
	global_load_dwordx4 v[54:57], v[4:5], off
	v_lshl_add_u64 v[4:5], v[4:5], 0, s[10:11]
	s_waitcnt vmcnt(23)
	v_cvt_pk_bf16_f32 v58, v58, v59
	v_cvt_pk_bf16_f32 v59, v60, v61
	global_store_dwordx2 v[6:7], v[58:59], off
	v_lshl_add_u64 v[6:7], v[6:7], 0, s[12:13]
	global_load_dwordx4 v[58:61], v[4:5], off
	v_lshl_add_u64 v[4:5], v[4:5], 0, s[10:11]
	s_waitcnt vmcnt(24)
	v_cvt_pk_bf16_f32 v62, v62, v63
	v_cvt_pk_bf16_f32 v63, v64, v65
	global_store_dwordx2 v[6:7], v[62:63], off
	v_lshl_add_u64 v[6:7], v[6:7], 0, s[12:13]
	global_load_dwordx4 v[62:65], v[4:5], off
	v_lshl_add_u64 v[4:5], v[4:5], 0, s[10:11]
	s_waitcnt vmcnt(25)
	v_cvt_pk_bf16_f32 v66, v66, v67
	v_cvt_pk_bf16_f32 v67, v68, v69
	global_store_dwordx2 v[6:7], v[66:67], off
	v_lshl_add_u64 v[6:7], v[6:7], 0, s[12:13]
	global_load_dwordx4 v[66:69], v[4:5], off
	v_lshl_add_u64 v[4:5], v[4:5], 0, s[10:11]
	s_waitcnt vmcnt(26)
	v_cvt_pk_bf16_f32 v70, v70, v71
	v_cvt_pk_bf16_f32 v71, v72, v73
	global_store_dwordx2 v[6:7], v[70:71], off
	v_lshl_add_u64 v[6:7], v[6:7], 0, s[12:13]
	global_load_dwordx4 v[70:73], v[4:5], off
	v_lshl_add_u64 v[4:5], v[4:5], 0, s[10:11]
	s_waitcnt vmcnt(27)
	v_cvt_pk_bf16_f32 v74, v74, v75
	v_cvt_pk_bf16_f32 v75, v76, v77
	global_store_dwordx2 v[6:7], v[74:75], off
	v_lshl_add_u64 v[6:7], v[6:7], 0, s[12:13]
	global_load_dwordx4 v[74:77], v[4:5], off
	v_lshl_add_u64 v[4:5], v[4:5], 0, s[10:11]
	s_waitcnt vmcnt(28)
	v_cvt_pk_bf16_f32 v78, v78, v79
	v_cvt_pk_bf16_f32 v79, v80, v81
	global_store_dwordx2 v[6:7], v[78:79], off
	v_lshl_add_u64 v[6:7], v[6:7], 0, s[12:13]
	global_load_dwordx4 v[78:81], v[4:5], off
	v_lshl_add_u64 v[4:5], v[4:5], 0, s[10:11]
	s_waitcnt vmcnt(29)
	v_cvt_pk_bf16_f32 v82, v82, v83
	v_cvt_pk_bf16_f32 v83, v84, v85
	global_store_dwordx2 v[6:7], v[82:83], off
	v_lshl_add_u64 v[6:7], v[6:7], 0, s[12:13]
	global_load_dwordx4 v[82:85], v[4:5], off
	v_lshl_add_u64 v[4:5], v[4:5], 0, s[10:11]
	s_waitcnt vmcnt(30)
	v_cvt_pk_bf16_f32 v86, v86, v87
	v_cvt_pk_bf16_f32 v87, v88, v89
	global_store_dwordx2 v[6:7], v[86:87], off
	v_lshl_add_u64 v[6:7], v[6:7], 0, s[12:13]
	global_load_dwordx4 v[86:89], v[4:5], off
	v_lshl_add_u64 v[4:5], v[4:5], 0, s[10:11]
	s_waitcnt vmcnt(30)
	v_cvt_pk_bf16_f32 v26, v26, v27
	v_cvt_pk_bf16_f32 v27, v28, v29
	global_store_dwordx2 v[6:7], v[26:27], off
	v_lshl_add_u64 v[6:7], v[6:7], 0, s[12:13]
	s_waitcnt vmcnt(29)
	v_cvt_pk_bf16_f32 v30, v30, v31
	v_cvt_pk_bf16_f32 v31, v32, v33
	global_store_dwordx2 v[6:7], v[30:31], off
	v_lshl_add_u64 v[6:7], v[6:7], 0, s[12:13]
	s_waitcnt vmcnt(28)
	v_cvt_pk_bf16_f32 v34, v34, v35
	v_cvt_pk_bf16_f32 v35, v36, v37
	global_store_dwordx2 v[6:7], v[34:35], off
	v_lshl_add_u64 v[6:7], v[6:7], 0, s[12:13]
	s_waitcnt vmcnt(27)
	v_cvt_pk_bf16_f32 v38, v38, v39
	v_cvt_pk_bf16_f32 v39, v40, v41
	global_store_dwordx2 v[6:7], v[38:39], off
	v_lshl_add_u64 v[6:7], v[6:7], 0, s[12:13]
	s_waitcnt vmcnt(26)
	v_cvt_pk_bf16_f32 v42, v42, v43
	v_cvt_pk_bf16_f32 v43, v44, v45
	global_store_dwordx2 v[6:7], v[42:43], off
	v_lshl_add_u64 v[6:7], v[6:7], 0, s[12:13]
	s_waitcnt vmcnt(25)
	v_cvt_pk_bf16_f32 v46, v46, v47
	v_cvt_pk_bf16_f32 v47, v48, v49
	global_store_dwordx2 v[6:7], v[46:47], off
	v_lshl_add_u64 v[6:7], v[6:7], 0, s[12:13]
	s_waitcnt vmcnt(24)
	v_cvt_pk_bf16_f32 v50, v50, v51
	v_cvt_pk_bf16_f32 v51, v52, v53
	global_store_dwordx2 v[6:7], v[50:51], off
	v_lshl_add_u64 v[6:7], v[6:7], 0, s[12:13]
	s_waitcnt vmcnt(23)
	v_cvt_pk_bf16_f32 v54, v54, v55
	v_cvt_pk_bf16_f32 v55, v56, v57
	global_store_dwordx2 v[6:7], v[54:55], off
	v_lshl_add_u64 v[6:7], v[6:7], 0, s[12:13]
	s_waitcnt vmcnt(22)
	v_cvt_pk_bf16_f32 v58, v58, v59
	v_cvt_pk_bf16_f32 v59, v60, v61
	global_store_dwordx2 v[6:7], v[58:59], off
	v_lshl_add_u64 v[6:7], v[6:7], 0, s[12:13]
	s_waitcnt vmcnt(21)
	v_cvt_pk_bf16_f32 v62, v62, v63
	v_cvt_pk_bf16_f32 v63, v64, v65
	global_store_dwordx2 v[6:7], v[62:63], off
	v_lshl_add_u64 v[6:7], v[6:7], 0, s[12:13]
	s_waitcnt vmcnt(20)
	v_cvt_pk_bf16_f32 v66, v66, v67
	v_cvt_pk_bf16_f32 v67, v68, v69
	global_store_dwordx2 v[6:7], v[66:67], off
	v_lshl_add_u64 v[6:7], v[6:7], 0, s[12:13]
	s_waitcnt vmcnt(19)
	v_cvt_pk_bf16_f32 v70, v70, v71
	v_cvt_pk_bf16_f32 v71, v72, v73
	global_store_dwordx2 v[6:7], v[70:71], off
	v_lshl_add_u64 v[6:7], v[6:7], 0, s[12:13]
	s_waitcnt vmcnt(18)
	v_cvt_pk_bf16_f32 v74, v74, v75
	v_cvt_pk_bf16_f32 v75, v76, v77
	global_store_dwordx2 v[6:7], v[74:75], off
	v_lshl_add_u64 v[6:7], v[6:7], 0, s[12:13]
	s_waitcnt vmcnt(17)
	v_cvt_pk_bf16_f32 v78, v78, v79
	v_cvt_pk_bf16_f32 v79, v80, v81
	global_store_dwordx2 v[6:7], v[78:79], off
	v_lshl_add_u64 v[6:7], v[6:7], 0, s[12:13]
	s_waitcnt vmcnt(16)
	v_cvt_pk_bf16_f32 v82, v82, v83
	v_cvt_pk_bf16_f32 v83, v84, v85
	global_store_dwordx2 v[6:7], v[82:83], off
	v_lshl_add_u64 v[6:7], v[6:7], 0, s[12:13]
	s_waitcnt vmcnt(15)
	v_cvt_pk_bf16_f32 v86, v86, v87
	v_cvt_pk_bf16_f32 v87, v88, v89
	global_store_dwordx2 v[6:7], v[86:87], off
	v_lshl_add_u64 v[6:7], v[6:7], 0, s[12:13]
